# v13 plus: phase-0 silu(c) staging loads issued together instead of nine dependent load-wait-store steps per item
# speedup vs baseline: 1.0231x; 1.0013x over previous
; __device__ __forceinline__ float silu_f(float x) { return x * __builtin_amdgcn_rcpf(1.0f + __expf(-x)); }
; __device__ __forceinline__ void phase_prep(const Params& p, LAS unsigned char* lds, bool do_mod) {
;     ...
;     for (int item = bid; do_mod && item < 576; item += G) {
;         const int cb = item >> 2, ks = item & 3;
;         for (int i = tid; i < 9 * 512; i += 512) { const int b = i >> 9, k = i & 511; const float cv = b < 8 ? p.c[b * DM + ks * 512 + k] : p.c_ctx[ks * 512 + k]; sv[i] = silu_f(cv); }
;         __syncthreads();
.LBB0_1384:
	v_mov_b32_e32 v7, v96
	v_lshlrev_b32_e32 v6, 2, v2
	v_lshl_add_u64 v[6:7], s[66:67], 0, v[6:7]
	s_mov_b64 s[4:5], 0x2000
	global_load_dword v8, v[6:7], off
	v_lshl_add_u64 v[6:7], v[6:7], 0, s[4:5]
	global_load_dword v9, v[6:7], off
	v_lshl_add_u64 v[6:7], v[6:7], 0, s[4:5]
	global_load_dword v10, v[6:7], off
	v_lshl_add_u64 v[6:7], v[6:7], 0, s[4:5]
	global_load_dword v11, v[6:7], off
	v_lshl_add_u64 v[6:7], v[6:7], 0, s[4:5]
	global_load_dword v12, v[6:7], off
	v_lshl_add_u64 v[6:7], v[6:7], 0, s[4:5]
	global_load_dword v13, v[6:7], off
	v_lshl_add_u64 v[6:7], v[6:7], 0, s[4:5]
	global_load_dword v14, v[6:7], off
	v_lshl_add_u64 v[6:7], v[6:7], 0, s[4:5]
	global_load_dword v15, v[6:7], off
	global_load_dword v16, v[0:1], off
	s_waitcnt vmcnt(8)
	v_mul_f32_e32 v17, 0xbfb8aa3b, v8
	s_waitcnt vmcnt(7)
	v_mul_f32_e32 v18, 0xbfb8aa3b, v9
	s_waitcnt vmcnt(6)
	v_mul_f32_e32 v19, 0xbfb8aa3b, v10
	s_waitcnt vmcnt(5)
	v_mul_f32_e32 v20, 0xbfb8aa3b, v11
	s_waitcnt vmcnt(4)
	v_mul_f32_e32 v21, 0xbfb8aa3b, v12
	s_waitcnt vmcnt(3)
	v_mul_f32_e32 v22, 0xbfb8aa3b, v13
	s_waitcnt vmcnt(2)
	v_mul_f32_e32 v23, 0xbfb8aa3b, v14
	s_waitcnt vmcnt(1)
	v_mul_f32_e32 v24, 0xbfb8aa3b, v15
	s_waitcnt vmcnt(0)
	v_mul_f32_e32 v25, 0xbfb8aa3b, v16
	v_exp_f32_e32 v17, v17
	v_exp_f32_e32 v18, v18
	v_exp_f32_e32 v19, v19
	v_exp_f32_e32 v20, v20
	v_exp_f32_e32 v21, v21
	v_exp_f32_e32 v22, v22
	v_exp_f32_e32 v23, v23
	v_exp_f32_e32 v24, v24
	v_exp_f32_e32 v25, v25
	v_add_f32_e32 v17, 1.0, v17
	v_add_f32_e32 v18, 1.0, v18
	v_add_f32_e32 v19, 1.0, v19
	v_add_f32_e32 v20, 1.0, v20
	v_add_f32_e32 v21, 1.0, v21
	v_add_f32_e32 v22, 1.0, v22
	v_add_f32_e32 v23, 1.0, v23
	v_add_f32_e32 v24, 1.0, v24
	v_add_f32_e32 v25, 1.0, v25
	v_rcp_f32_e32 v17, v17
	v_rcp_f32_e32 v18, v18
	v_rcp_f32_e32 v19, v19
	v_rcp_f32_e32 v20, v20
	v_rcp_f32_e32 v21, v21
	v_rcp_f32_e32 v22, v22
	v_rcp_f32_e32 v23, v23
	v_rcp_f32_e32 v24, v24
	v_rcp_f32_e32 v25, v25
	v_mul_f32_e32 v8, v8, v17
	v_mul_f32_e32 v9, v9, v18
	v_mul_f32_e32 v10, v10, v19
	v_mul_f32_e32 v11, v11, v20
	v_mul_f32_e32 v12, v12, v21
	v_mul_f32_e32 v13, v13, v22
	v_mul_f32_e32 v14, v14, v23
	v_mul_f32_e32 v15, v15, v24
	v_mul_f32_e32 v16, v16, v25
	ds_write_b32 v3, v8
	ds_write_b32 v3, v9 offset:2048
	ds_write_b32 v3, v10 offset:4096
	ds_write_b32 v3, v11 offset:6144
	ds_write_b32 v3, v12 offset:8192
	ds_write_b32 v3, v13 offset:10240
	ds_write_b32 v3, v14 offset:12288
	ds_write_b32 v3, v15 offset:14336
	ds_write_b32 v3, v16 offset:16384
